# MLP1 and w_in GEMM tile loops: first K-iteration after an epilogue uses vmcnt(24) in phases 1-3 so the 16 epilogue stores drain under the MFMAs (flag in s32)
# baseline (speedup 1.0000x reference)
.LBB0_472:
	v_lshrrev_b32_e32 v16, 1, v6
	v_and_b32_e32 v16, 24, v16
	s_sext_i32_i16 s57, s6
	s_add_u32 s6, s0, 0x1b400000
	v_and_b32_e32 v7, 15, v6
	v_lshlrev_b32_e32 v17, 1, v16
	v_lshlrev_b32_e32 v6, 2, v6
	s_addc_u32 s7, s1, 0
	v_lshl_or_b32 v142, s10, 6, v7
	v_lshl_or_b32 v7, v7, 6, v17
	s_lshl_b32 s0, s10, 13
	v_and_b32_e32 v6, 32, v6
	v_bitop3_b32 v143, v7, s0, v6 bitop3:0xde
	s_lshl_b32 s0, s9, 5
	s_and_b32 s10, s0, 0x60
	v_lshl_add_u64 v[8:9], s[20:21], 0, v[160:161]
	v_mov_b32_e32 v129, v161
	s_lshl_b32 s0, s10, 7
	s_add_i32 s44, s31, 0x18000
	v_lshl_add_u64 v[10:11], s[20:21], 0, v[128:129]
	v_mov_b32_e32 v133, v161
	v_bitop3_b32 v144, v7, s0, v6 bitop3:0xde
	v_lshl_add_u64 v[6:7], v[8:9], 0, s[40:41]
	s_mov_b32 m0, s44
	s_add_i32 s45, s31, 0x1a000
	v_lshl_add_u64 v[12:13], s[22:23], 0, v[132:133]
	v_mov_b32_e32 v131, v161
	s_waitcnt vmcnt(2)
	s_barrier
	global_load_lds_dwordx4 v[6:7], off
	v_lshl_add_u64 v[6:7], v[10:11], 0, s[40:41]
	s_mov_b32 m0, s45
	s_add_i32 s46, s31, 0x8000
	s_add_i32 s47, s31, 0xa000
	v_lshl_add_u64 v[14:15], s[22:23], 0, v[130:131]
	global_load_lds_dwordx4 v[6:7], off
	v_lshl_add_u64 v[6:7], v[12:13], 0, s[40:41]
	s_mov_b32 m0, s46
	s_add_u32 s0, s20, 0x80080
	global_load_lds_dwordx4 v[6:7], off
	v_lshl_add_u64 v[6:7], v[14:15], 0, s[40:41]
	s_mov_b32 m0, s47
	s_addc_u32 s1, s21, 0
	s_add_i32 s54, s31, 0x1c000
	global_load_lds_dwordx4 v[6:7], off
	v_lshl_add_u64 v[6:7], s[0:1], 0, v[160:161]
	s_mov_b32 m0, s54
	s_add_i32 s55, s31, 0x1e000
	global_load_lds_dwordx4 v[6:7], off
	v_lshl_add_u64 v[6:7], s[0:1], 0, v[128:129]
	s_mov_b32 m0, s55
	s_cmpk_lt_u32 s8, 0x100
	global_load_lds_dwordx4 v[6:7], off
	v_lshlrev_b32_e32 v6, 15, v0
	v_and_b32_e32 v6, 0xffff0000, v6
	v_lshl_add_u32 v1, v1, 12, v6
	v_and_b32_e32 v0, 1, v0
	v_lshl_or_b32 v0, v0, 6, v1
	v_lshl_add_u32 v134, v2, 1, v0
	v_lshlrev_b32_e32 v0, 15, v4
	v_and_b32_e32 v0, 0xffff0000, v0
	s_waitcnt vmcnt(6)
	v_lshl_add_u32 v0, v3, 12, v0
	v_and_b32_e32 v1, 1, v4
	v_lshl_or_b32 v0, v1, 6, v0
	s_cselect_b64 s[8:9], -1, 0
	v_or_b32_e32 v145, s10, v16
	v_mov_b32_e32 v135, v161
	v_lshl_add_u32 v136, v5, 1, v0
	v_mov_b32_e32 v137, v161
	s_mov_b32 s56, 0
	s_barrier
	s_mov_b32 s32, 0
	s_branch .LBB0_475

.LBB0_474:
	s_andn2_b64 vcc, exec, s[0:1]
	s_mov_b32 s57, s10
	s_mov_b32 s14, s12
	s_mov_b64 s[20:21], s[18:19]
	s_mov_b64 s[22:23], s[16:17]
	s_cbranch_vccz .LBB0_484
	s_mov_b32 s32, 1

.LBB0_478:
	v_or_b32_e32 v138, 0x10000, v144
	v_add_u32_e32 v146, 0x10400, v144
	v_add_u32_e32 v150, 0x10800, v144
	v_add_u32_e32 v154, 0x10c00, v144
	v_or_b32_e32 v158, 0x14000, v144
	ds_read_b128 v[138:141], v138
	ds_read_b128 v[146:149], v146
	ds_read_b128 v[150:153], v150
	ds_read_b128 v[154:157], v154
	v_add_u32_e32 v159, 0x14400, v144
	ds_read_b128 v[170:173], v158
	ds_read_b128 v[174:177], v159
	v_add_u32_e32 v158, 0x14800, v144
	v_add_u32_e32 v159, 0x14c00, v144
	ds_read_b128 v[178:181], v158
	ds_read_b128 v[182:185], v159
	s_add_u32 s22, s20, 0xfff80080
	s_addc_u32 s23, s21, -1
	s_cmp_eq_u32 s62, 28
	s_cselect_b32 s25, s13, s23
	s_cselect_b32 s24, s58, s22
	s_cselect_b32 s23, s11, s61
	s_cselect_b32 s22, s59, s60
	v_lshl_add_u64 v[158:159], s[20:21], 0, v[136:137]
	s_add_i32 m0, s31, 0xc000
	ds_read_b128 v[186:189], v143
	ds_read_b128 v[198:201], v143 offset:1024
	ds_read_b128 v[210:213], v143 offset:2048
	ds_read_b128 v[214:217], v143 offset:3072
	ds_read_b128 v[218:221], v143 offset:4096
	ds_read_b128 v[222:225], v143 offset:5120
	ds_read_b128 v[226:229], v143 offset:6144
	ds_read_b128 v[230:233], v143 offset:7168
	global_load_lds_dwordx4 v[158:159], off
	v_lshl_add_u64 v[158:159], s[20:21], 0, v[134:135]
	s_add_i32 m0, s31, 0xe000
	s_nop 0
	global_load_lds_dwordx4 v[158:159], off
	s_cmp_eq_u32 s32, 0
	s_cbranch_scc0 .Lmy_g4_alt0
	s_waitcnt vmcnt(8)
.Lmy_g4_bk0:
	s_waitcnt lgkmcnt(0)
	s_barrier
	s_setprio 1
	s_waitcnt lgkmcnt(0)
	v_mfma_f32_16x16x32_bf16 v[124:127], v[138:141], v[186:189], v[124:127]
	v_mfma_f32_16x16x32_bf16 v[120:123], v[150:153], v[186:189], v[120:123]
	v_mfma_f32_16x16x32_bf16 v[116:119], v[138:141], v[210:213], v[116:119]
	v_mfma_f32_16x16x32_bf16 v[108:111], v[150:153], v[210:213], v[108:111]
	v_mfma_f32_16x16x32_bf16 v[100:103], v[138:141], v[218:221], v[100:103]
	v_mfma_f32_16x16x32_bf16 v[92:95], v[150:153], v[218:221], v[92:95]
	v_mfma_f32_16x16x32_bf16 v[84:87], v[138:141], v[226:229], v[84:87]
	v_mfma_f32_16x16x32_bf16 v[76:79], v[150:153], v[226:229], v[76:79]
	v_mfma_f32_16x16x32_bf16 v[124:127], v[146:149], v[198:201], v[124:127]
	v_mfma_f32_16x16x32_bf16 v[120:123], v[154:157], v[198:201], v[120:123]
	v_mfma_f32_16x16x32_bf16 v[116:119], v[146:149], v[214:217], v[116:119]
	v_mfma_f32_16x16x32_bf16 v[108:111], v[154:157], v[214:217], v[108:111]
	v_mfma_f32_16x16x32_bf16 v[100:103], v[146:149], v[222:225], v[100:103]
	v_mfma_f32_16x16x32_bf16 v[92:95], v[154:157], v[222:225], v[92:95]
	v_mfma_f32_16x16x32_bf16 v[84:87], v[146:149], v[230:233], v[84:87]
	v_mfma_f32_16x16x32_bf16 v[76:79], v[154:157], v[230:233], v[76:79]
	s_setprio 0
	s_setprio 1
	v_mfma_f32_16x16x32_bf16 v[112:115], v[170:173], v[186:189], v[112:115]
	v_mfma_f32_16x16x32_bf16 v[104:107], v[178:181], v[186:189], v[104:107]
	v_mfma_f32_16x16x32_bf16 v[96:99], v[170:173], v[210:213], v[96:99]
	v_mfma_f32_16x16x32_bf16 v[88:91], v[178:181], v[210:213], v[88:91]
	v_mfma_f32_16x16x32_bf16 v[80:83], v[170:173], v[218:221], v[80:83]
	v_mfma_f32_16x16x32_bf16 v[72:75], v[178:181], v[218:221], v[72:75]
	v_mfma_f32_16x16x32_bf16 v[68:71], v[170:173], v[226:229], v[68:71]
	v_mfma_f32_16x16x32_bf16 v[64:67], v[178:181], v[226:229], v[64:67]
	v_mfma_f32_16x16x32_bf16 v[112:115], v[174:177], v[198:201], v[112:115]
	v_mfma_f32_16x16x32_bf16 v[104:107], v[182:185], v[198:201], v[104:107]
	v_mfma_f32_16x16x32_bf16 v[96:99], v[174:177], v[214:217], v[96:99]
	v_mfma_f32_16x16x32_bf16 v[88:91], v[182:185], v[214:217], v[88:91]
	v_mfma_f32_16x16x32_bf16 v[80:83], v[174:177], v[222:225], v[80:83]
	v_mfma_f32_16x16x32_bf16 v[72:75], v[182:185], v[222:225], v[72:75]
	v_mfma_f32_16x16x32_bf16 v[68:71], v[174:177], v[230:233], v[68:71]
	v_mfma_f32_16x16x32_bf16 v[64:67], v[182:185], v[230:233], v[64:67]
	s_setprio 0
	s_barrier
	s_mov_b32 m0, s15
	v_lshl_add_u64 v[158:159], s[22:23], 0, v[160:161]
	s_add_u32 s64, s22, 0x80000
	ds_read_b128 v[186:189], v143 offset:16384
	ds_read_b128 v[198:201], v143 offset:17408
	ds_read_b128 v[210:213], v143 offset:18432
	ds_read_b128 v[214:217], v143 offset:19456
	ds_read_b128 v[218:221], v143 offset:20480
	ds_read_b128 v[222:225], v143 offset:21504
	ds_read_b128 v[226:229], v143 offset:22528
	ds_read_b128 v[230:233], v143 offset:23552
	global_load_lds_dwordx4 v[158:159], off
	v_lshl_add_u64 v[190:191], s[22:23], 0, v[128:129]
	s_mov_b32 m0, s35
	s_addc_u32 s65, s23, 0
	global_load_lds_dwordx4 v[190:191], off
	v_lshl_add_u64 v[202:203], s[64:65], 0, v[160:161]
	s_mov_b32 m0, s36
	v_lshl_add_u64 v[204:205], s[24:25], 0, v[130:131]
	global_load_lds_dwordx4 v[202:203], off
	v_lshl_add_u64 v[202:203], s[64:65], 0, v[128:129]
	s_mov_b32 m0, s37
	s_nop 0
	global_load_lds_dwordx4 v[202:203], off
	v_lshl_add_u64 v[202:203], s[24:25], 0, v[132:133]
	s_mov_b32 m0, s31
	s_nop 0
	global_load_lds_dwordx4 v[202:203], off
	s_mov_b32 m0, s38
	s_nop 0
	global_load_lds_dwordx4 v[204:205], off
	s_cmp_eq_u32 s32, 0
	s_cbranch_scc0 .Lmy_g4_alt1
	s_waitcnt vmcnt(8)
.Lmy_g4_bk1:
	s_waitcnt lgkmcnt(0)
	s_barrier
	s_setprio 1
	s_waitcnt lgkmcnt(0)
	v_mfma_f32_16x16x32_bf16 v[60:63], v[138:141], v[186:189], v[60:63]
	v_mfma_f32_16x16x32_bf16 v[56:59], v[150:153], v[186:189], v[56:59]
	v_mfma_f32_16x16x32_bf16 v[52:55], v[138:141], v[210:213], v[52:55]
	v_mfma_f32_16x16x32_bf16 v[44:47], v[150:153], v[210:213], v[44:47]
	v_mfma_f32_16x16x32_bf16 v[36:39], v[138:141], v[218:221], v[36:39]
	v_mfma_f32_16x16x32_bf16 v[28:31], v[150:153], v[218:221], v[28:31]
	v_mfma_f32_16x16x32_bf16 v[20:23], v[138:141], v[226:229], v[20:23]
	v_mfma_f32_16x16x32_bf16 v[12:15], v[150:153], v[226:229], v[12:15]
	v_mfma_f32_16x16x32_bf16 v[60:63], v[146:149], v[198:201], v[60:63]
	v_mfma_f32_16x16x32_bf16 v[56:59], v[154:157], v[198:201], v[56:59]
	v_mfma_f32_16x16x32_bf16 v[52:55], v[146:149], v[214:217], v[52:55]
	v_mfma_f32_16x16x32_bf16 v[44:47], v[154:157], v[214:217], v[44:47]
	v_mfma_f32_16x16x32_bf16 v[36:39], v[146:149], v[222:225], v[36:39]
	v_mfma_f32_16x16x32_bf16 v[28:31], v[154:157], v[222:225], v[28:31]
	v_mfma_f32_16x16x32_bf16 v[20:23], v[146:149], v[230:233], v[20:23]
	v_mfma_f32_16x16x32_bf16 v[12:15], v[154:157], v[230:233], v[12:15]
	s_setprio 0
	s_setprio 1
	v_mfma_f32_16x16x32_bf16 v[48:51], v[170:173], v[186:189], v[48:51]
	v_mfma_f32_16x16x32_bf16 v[40:43], v[178:181], v[186:189], v[40:43]
	v_mfma_f32_16x16x32_bf16 v[32:35], v[170:173], v[210:213], v[32:35]
	v_mfma_f32_16x16x32_bf16 v[24:27], v[178:181], v[210:213], v[24:27]
	v_mfma_f32_16x16x32_bf16 v[16:19], v[170:173], v[218:221], v[16:19]
	v_mfma_f32_16x16x32_bf16 v[8:11], v[178:181], v[218:221], v[8:11]
	v_mfma_f32_16x16x32_bf16 v[4:7], v[170:173], v[226:229], v[4:7]
	v_mfma_f32_16x16x32_bf16 v[0:3], v[178:181], v[226:229], v[0:3]
	v_mfma_f32_16x16x32_bf16 v[48:51], v[174:177], v[198:201], v[48:51]
	v_mfma_f32_16x16x32_bf16 v[40:43], v[182:185], v[198:201], v[40:43]
	v_mfma_f32_16x16x32_bf16 v[32:35], v[174:177], v[214:217], v[32:35]
	v_mfma_f32_16x16x32_bf16 v[24:27], v[182:185], v[214:217], v[24:27]
	v_mfma_f32_16x16x32_bf16 v[16:19], v[174:177], v[222:225], v[16:19]
	v_mfma_f32_16x16x32_bf16 v[8:11], v[182:185], v[222:225], v[8:11]
	v_mfma_f32_16x16x32_bf16 v[4:7], v[174:177], v[230:233], v[4:7]
	v_mfma_f32_16x16x32_bf16 v[0:3], v[182:185], v[230:233], v[0:3]
	s_setprio 0
	s_barrier
	v_or_b32_e32 v138, 0x18000, v144
	v_add_u32_e32 v146, 0x18400, v144
	v_add_u32_e32 v150, 0x18800, v144
	v_add_u32_e32 v154, 0x18c00, v144
	v_or_b32_e32 v170, 0x1c000, v144
	v_add_u32_e32 v174, 0x1c400, v144
	v_add_u32_e32 v178, 0x1c800, v144
	v_add_u32_e32 v182, 0x1cc00, v144
	ds_read_b128 v[138:141], v138
	ds_read_b128 v[146:149], v146
	ds_read_b128 v[150:153], v150
	ds_read_b128 v[154:157], v154
	ds_read_b128 v[170:173], v170
	ds_read_b128 v[174:177], v174
	ds_read_b128 v[178:181], v178
	ds_read_b128 v[182:185], v182
	s_add_u32 s24, s24, 0x80000
	s_addc_u32 s25, s25, 0
	s_mov_b32 m0, s42
	v_lshl_add_u64 v[234:235], s[24:25], 0, v[132:133]
	ds_read_b128 v[186:189], v143 offset:32768
	ds_read_b128 v[198:201], v143 offset:33792
	ds_read_b128 v[210:213], v143 offset:34816
	ds_read_b128 v[214:217], v143 offset:35840
	ds_read_b128 v[218:221], v143 offset:36864
	ds_read_b128 v[222:225], v143 offset:37888
	ds_read_b128 v[226:229], v143 offset:38912
	ds_read_b128 v[230:233], v143 offset:39936
	global_load_lds_dwordx4 v[234:235], off
	v_lshl_add_u64 v[234:235], s[24:25], 0, v[130:131]
	s_mov_b32 m0, s43
	s_nop 0
	global_load_lds_dwordx4 v[234:235], off
	s_cmp_eq_u32 s32, 0
	s_cbranch_scc0 .Lmy_g4_alt2
	s_waitcnt vmcnt(8)
.Lmy_g4_bk2:
	s_waitcnt lgkmcnt(0)
	s_barrier
	s_setprio 1
	s_waitcnt lgkmcnt(0)
	v_mfma_f32_16x16x32_bf16 v[124:127], v[138:141], v[186:189], v[124:127]
	v_mfma_f32_16x16x32_bf16 v[120:123], v[150:153], v[186:189], v[120:123]
	v_mfma_f32_16x16x32_bf16 v[116:119], v[138:141], v[210:213], v[116:119]
	v_mfma_f32_16x16x32_bf16 v[108:111], v[150:153], v[210:213], v[108:111]
	v_mfma_f32_16x16x32_bf16 v[100:103], v[138:141], v[218:221], v[100:103]
	v_mfma_f32_16x16x32_bf16 v[92:95], v[150:153], v[218:221], v[92:95]
	v_mfma_f32_16x16x32_bf16 v[84:87], v[138:141], v[226:229], v[84:87]
	v_mfma_f32_16x16x32_bf16 v[76:79], v[150:153], v[226:229], v[76:79]
	v_mfma_f32_16x16x32_bf16 v[124:127], v[146:149], v[198:201], v[124:127]
	v_mfma_f32_16x16x32_bf16 v[120:123], v[154:157], v[198:201], v[120:123]
	v_mfma_f32_16x16x32_bf16 v[116:119], v[146:149], v[214:217], v[116:119]
	v_mfma_f32_16x16x32_bf16 v[108:111], v[154:157], v[214:217], v[108:111]
	v_mfma_f32_16x16x32_bf16 v[100:103], v[146:149], v[222:225], v[100:103]
	v_mfma_f32_16x16x32_bf16 v[92:95], v[154:157], v[222:225], v[92:95]
	v_mfma_f32_16x16x32_bf16 v[84:87], v[146:149], v[230:233], v[84:87]
	v_mfma_f32_16x16x32_bf16 v[76:79], v[154:157], v[230:233], v[76:79]
	s_setprio 0
	s_setprio 1
	v_mfma_f32_16x16x32_bf16 v[112:115], v[170:173], v[186:189], v[112:115]
	v_mfma_f32_16x16x32_bf16 v[104:107], v[178:181], v[186:189], v[104:107]
	v_mfma_f32_16x16x32_bf16 v[96:99], v[170:173], v[210:213], v[96:99]
	v_mfma_f32_16x16x32_bf16 v[88:91], v[178:181], v[210:213], v[88:91]
	v_mfma_f32_16x16x32_bf16 v[80:83], v[170:173], v[218:221], v[80:83]
	v_mfma_f32_16x16x32_bf16 v[72:75], v[178:181], v[218:221], v[72:75]
	v_mfma_f32_16x16x32_bf16 v[68:71], v[170:173], v[226:229], v[68:71]
	v_mfma_f32_16x16x32_bf16 v[64:67], v[178:181], v[226:229], v[64:67]
	v_mfma_f32_16x16x32_bf16 v[112:115], v[174:177], v[198:201], v[112:115]
	v_mfma_f32_16x16x32_bf16 v[104:107], v[182:185], v[198:201], v[104:107]
	v_mfma_f32_16x16x32_bf16 v[96:99], v[174:177], v[214:217], v[96:99]
	v_mfma_f32_16x16x32_bf16 v[88:91], v[182:185], v[214:217], v[88:91]
	v_mfma_f32_16x16x32_bf16 v[80:83], v[174:177], v[222:225], v[80:83]
	v_mfma_f32_16x16x32_bf16 v[72:75], v[182:185], v[222:225], v[72:75]
	v_mfma_f32_16x16x32_bf16 v[68:71], v[174:177], v[230:233], v[68:71]
	v_mfma_f32_16x16x32_bf16 v[64:67], v[182:185], v[230:233], v[64:67]
	s_setprio 0
	s_barrier
	s_mov_b32 m0, s44
	v_lshl_add_u64 v[158:159], v[158:159], 0, s[40:41]
	s_add_u32 s22, s22, 0x80080
	ds_read_b128 v[186:189], v143 offset:49152
	ds_read_b128 v[198:201], v143 offset:50176
	ds_read_b128 v[210:213], v143 offset:51200
	ds_read_b128 v[214:217], v143 offset:52224
	ds_read_b128 v[218:221], v143 offset:53248
	ds_read_b128 v[222:225], v143 offset:54272
	ds_read_b128 v[226:229], v143 offset:55296
	ds_read_b128 v[230:233], v143 offset:56320
	global_load_lds_dwordx4 v[158:159], off
	v_lshl_add_u64 v[158:159], v[190:191], 0, s[40:41]
	s_mov_b32 m0, s45
	s_addc_u32 s23, s23, 0
	global_load_lds_dwordx4 v[158:159], off
	v_lshl_add_u64 v[158:159], s[22:23], 0, v[160:161]
	s_mov_b32 m0, s54
	s_nop 0
	global_load_lds_dwordx4 v[158:159], off
	v_lshl_add_u64 v[158:159], s[22:23], 0, v[128:129]
	s_mov_b32 m0, s55
	s_nop 0
	global_load_lds_dwordx4 v[158:159], off
	v_lshl_add_u64 v[158:159], v[202:203], 0, s[40:41]
	s_mov_b32 m0, s46
	s_nop 0
	global_load_lds_dwordx4 v[158:159], off
	v_lshl_add_u64 v[158:159], v[204:205], 0, s[40:41]
	s_mov_b32 m0, s47
	s_nop 0
	global_load_lds_dwordx4 v[158:159], off
	s_waitcnt vmcnt(8)
	s_waitcnt lgkmcnt(0)
	s_barrier
	s_setprio 1
	s_waitcnt lgkmcnt(0)
	v_mfma_f32_16x16x32_bf16 v[60:63], v[138:141], v[186:189], v[60:63]
	v_mfma_f32_16x16x32_bf16 v[56:59], v[150:153], v[186:189], v[56:59]
	v_mfma_f32_16x16x32_bf16 v[52:55], v[138:141], v[210:213], v[52:55]
	v_mfma_f32_16x16x32_bf16 v[44:47], v[150:153], v[210:213], v[44:47]
	v_mfma_f32_16x16x32_bf16 v[36:39], v[138:141], v[218:221], v[36:39]
	v_mfma_f32_16x16x32_bf16 v[28:31], v[150:153], v[218:221], v[28:31]
	v_mfma_f32_16x16x32_bf16 v[20:23], v[138:141], v[226:229], v[20:23]
	v_mfma_f32_16x16x32_bf16 v[12:15], v[150:153], v[226:229], v[12:15]
	v_mfma_f32_16x16x32_bf16 v[60:63], v[146:149], v[198:201], v[60:63]
	v_mfma_f32_16x16x32_bf16 v[56:59], v[154:157], v[198:201], v[56:59]
	v_mfma_f32_16x16x32_bf16 v[52:55], v[146:149], v[214:217], v[52:55]
	v_mfma_f32_16x16x32_bf16 v[44:47], v[154:157], v[214:217], v[44:47]
	v_mfma_f32_16x16x32_bf16 v[36:39], v[146:149], v[222:225], v[36:39]
	v_mfma_f32_16x16x32_bf16 v[28:31], v[154:157], v[222:225], v[28:31]
	v_mfma_f32_16x16x32_bf16 v[20:23], v[146:149], v[230:233], v[20:23]
	v_mfma_f32_16x16x32_bf16 v[12:15], v[154:157], v[230:233], v[12:15]
	s_setprio 0
	s_setprio 1
	v_mfma_f32_16x16x32_bf16 v[48:51], v[170:173], v[186:189], v[48:51]
	v_mfma_f32_16x16x32_bf16 v[40:43], v[178:181], v[186:189], v[40:43]
	v_mfma_f32_16x16x32_bf16 v[32:35], v[170:173], v[210:213], v[32:35]
	v_mfma_f32_16x16x32_bf16 v[24:27], v[178:181], v[210:213], v[24:27]
	v_mfma_f32_16x16x32_bf16 v[16:19], v[170:173], v[218:221], v[16:19]
	v_mfma_f32_16x16x32_bf16 v[8:11], v[178:181], v[218:221], v[8:11]
	v_mfma_f32_16x16x32_bf16 v[4:7], v[170:173], v[226:229], v[4:7]
	v_mfma_f32_16x16x32_bf16 v[0:3], v[178:181], v[226:229], v[0:3]
	v_mfma_f32_16x16x32_bf16 v[48:51], v[174:177], v[198:201], v[48:51]
	v_mfma_f32_16x16x32_bf16 v[40:43], v[182:185], v[198:201], v[40:43]
	v_mfma_f32_16x16x32_bf16 v[32:35], v[174:177], v[214:217], v[32:35]
	v_mfma_f32_16x16x32_bf16 v[24:27], v[182:185], v[214:217], v[24:27]
	v_mfma_f32_16x16x32_bf16 v[16:19], v[174:177], v[222:225], v[16:19]
	v_mfma_f32_16x16x32_bf16 v[8:11], v[182:185], v[222:225], v[8:11]
	v_mfma_f32_16x16x32_bf16 v[4:7], v[174:177], v[230:233], v[4:7]
	v_mfma_f32_16x16x32_bf16 v[0:3], v[182:185], v[230:233], v[0:3]
	s_setprio 0
	s_barrier
	s_add_i32 s62, s62, 2
	s_add_u32 s60, s60, 0x100
	s_addc_u32 s61, s61, 0
	s_add_u32 s20, s20, 0x100
	s_addc_u32 s21, s21, 0
	s_mov_b32 s32, 0
	s_cmp_gt_u32 s62, 29
	s_cbranch_scc0 .LBB0_478
	s_branch .Lmy_g4_cont
.Lmy_g4_alt0:
	s_waitcnt vmcnt(24)
	s_branch .Lmy_g4_bk0

.Lmy_g4_cont:
	s_and_b64 vcc, exec, s[8:9]
	s_cbranch_vccz .LBB0_481
	s_barrier
.LBB0_481:
	v_lshl_or_b32 v140, s57, 8, v145
	v_lshl_add_u32 v148, s14, 8, v142
	v_ashrrev_i32_e32 v141, 31, v140
	v_mov_b64_e32 v[138:139], s[6:7]
	v_mad_i64_i32 v[146:147], s[20:21], v148, s33, v[138:139]
	v_lshlrev_b64 v[140:141], 1, v[140:141]
	v_lshl_add_u64 v[146:147], v[146:147], 0, v[140:141]
	v_cvt_pk_bf16_f32 v124, v124, v125
	v_cvt_pk_bf16_f32 v125, v126, v127
	v_cvt_pk_bf16_f32 v126, v120, v121
	v_cvt_pk_bf16_f32 v127, v122, v123
	global_store_dwordx4 v[146:147], v[124:127], off
	v_cvt_pk_bf16_f32 v112, v112, v113
	v_cvt_pk_bf16_f32 v113, v114, v115
	v_cvt_pk_bf16_f32 v114, v104, v105
	v_or_b32_e32 v104, 16, v148
	v_mad_i64_i32 v[104:105], s[20:21], v104, s33, v[138:139]
	v_cvt_pk_bf16_f32 v115, v106, v107
	global_store_dwordx4 v[146:147], v[112:115], off offset:256
	v_readlane_b32 s58, v255, 13
	v_readlane_b32 s62, v253, 42
	v_lshl_add_u64 v[112:113], v[104:105], 0, v[140:141]
	v_cvt_pk_bf16_f32 v104, v116, v117
	v_cvt_pk_bf16_f32 v105, v118, v119
	v_cvt_pk_bf16_f32 v106, v108, v109
	v_cvt_pk_bf16_f32 v107, v110, v111
	global_store_dwordx4 v[112:113], v[104:107], off
	v_cvt_pk_bf16_f32 v96, v96, v97
	v_cvt_pk_bf16_f32 v97, v98, v99
	v_cvt_pk_bf16_f32 v98, v88, v89
	v_or_b32_e32 v88, 32, v148
	v_mad_i64_i32 v[88:89], s[20:21], v88, s33, v[138:139]
	v_cvt_pk_bf16_f32 v99, v90, v91
	global_store_dwordx4 v[112:113], v[96:99], off offset:256
	s_andn2_b64 vcc, exec, s[0:1]
	s_mov_b64 s[0:1], -1
	v_lshl_add_u64 v[96:97], v[88:89], 0, v[140:141]
	v_cvt_pk_bf16_f32 v88, v100, v101
	v_cvt_pk_bf16_f32 v89, v102, v103
	v_cvt_pk_bf16_f32 v90, v92, v93
	v_cvt_pk_bf16_f32 v91, v94, v95
	global_store_dwordx4 v[96:97], v[88:91], off
	v_cvt_pk_bf16_f32 v80, v80, v81
	v_cvt_pk_bf16_f32 v81, v82, v83
	v_cvt_pk_bf16_f32 v82, v72, v73
	v_or_b32_e32 v72, 48, v148
	v_mad_i64_i32 v[72:73], s[20:21], v72, s33, v[138:139]
	v_cvt_pk_bf16_f32 v83, v74, v75
	global_store_dwordx4 v[96:97], v[80:83], off offset:256
	v_readlane_b32 s59, v255, 14
	s_movk_i32 s60, 0x2000
	v_lshl_add_u64 v[80:81], v[72:73], 0, v[140:141]
	v_cvt_pk_bf16_f32 v72, v84, v85
	v_cvt_pk_bf16_f32 v73, v86, v87
	v_cvt_pk_bf16_f32 v74, v76, v77
	v_cvt_pk_bf16_f32 v75, v78, v79
	global_store_dwordx4 v[80:81], v[72:75], off
	v_cvt_pk_bf16_f32 v68, v68, v69
	v_cvt_pk_bf16_f32 v69, v70, v71
	v_cvt_pk_bf16_f32 v70, v64, v65
	v_add_u32_e32 v64, 0x80, v148
	v_mad_i64_i32 v[64:65], s[20:21], v64, s33, v[138:139]
	v_lshl_add_u64 v[64:65], v[64:65], 0, v[140:141]
	v_cvt_pk_bf16_f32 v71, v66, v67
	global_store_dwordx4 v[80:81], v[68:71], off offset:256
	v_cvt_pk_bf16_f32 v60, v60, v61
	v_cvt_pk_bf16_f32 v61, v62, v63
	v_cvt_pk_bf16_f32 v62, v56, v57
	v_cvt_pk_bf16_f32 v63, v58, v59
	global_store_dwordx4 v[64:65], v[60:63], off
	v_cvt_pk_bf16_f32 v48, v48, v49
	v_cvt_pk_bf16_f32 v49, v50, v51
	v_cvt_pk_bf16_f32 v50, v40, v41
	v_add_u32_e32 v40, 0x90, v148
	v_mad_i64_i32 v[40:41], s[20:21], v40, s33, v[138:139]
	v_cvt_pk_bf16_f32 v51, v42, v43
	global_store_dwordx4 v[64:65], v[48:51], off offset:256
	v_readlane_b32 s63, v253, 43
	s_nop 0
	v_lshl_add_u64 v[48:49], v[40:41], 0, v[140:141]
	v_cvt_pk_bf16_f32 v40, v52, v53
	v_cvt_pk_bf16_f32 v41, v54, v55
	v_cvt_pk_bf16_f32 v42, v44, v45
	v_cvt_pk_bf16_f32 v43, v46, v47
	global_store_dwordx4 v[48:49], v[40:43], off
	v_cvt_pk_bf16_f32 v32, v32, v33
	v_cvt_pk_bf16_f32 v33, v34, v35
	v_cvt_pk_bf16_f32 v34, v24, v25
	v_add_u32_e32 v24, 0xa0, v148
	v_mad_i64_i32 v[24:25], s[20:21], v24, s33, v[138:139]
	v_cvt_pk_bf16_f32 v35, v26, v27
	global_store_dwordx4 v[48:49], v[32:35], off offset:256
	s_nop 1
	v_lshl_add_u64 v[32:33], v[24:25], 0, v[140:141]
	v_cvt_pk_bf16_f32 v24, v36, v37
	v_cvt_pk_bf16_f32 v25, v38, v39
	v_cvt_pk_bf16_f32 v26, v28, v29
	v_cvt_pk_bf16_f32 v27, v30, v31
	global_store_dwordx4 v[32:33], v[24:27], off
	v_cvt_pk_bf16_f32 v16, v16, v17
	v_cvt_pk_bf16_f32 v17, v18, v19
	v_cvt_pk_bf16_f32 v18, v8, v9
	v_add_u32_e32 v8, 0xb0, v148
	v_mad_i64_i32 v[8:9], s[20:21], v8, s33, v[138:139]
	v_cvt_pk_bf16_f32 v19, v10, v11
	global_store_dwordx4 v[32:33], v[16:19], off offset:256
	s_nop 1
	v_lshl_add_u64 v[16:17], v[8:9], 0, v[140:141]
	v_cvt_pk_bf16_f32 v8, v20, v21
	v_cvt_pk_bf16_f32 v9, v22, v23
	v_cvt_pk_bf16_f32 v10, v12, v13
	v_cvt_pk_bf16_f32 v11, v14, v15
	global_store_dwordx4 v[16:17], v[8:11], off
	v_cvt_pk_bf16_f32 v4, v4, v5
	v_cvt_pk_bf16_f32 v5, v6, v7
	v_cvt_pk_bf16_f32 v6, v0, v1
	v_cvt_pk_bf16_f32 v7, v2, v3
	global_store_dwordx4 v[16:17], v[4:7], off offset:256
	s_cbranch_vccnz .LBB0_474
	s_andn2_b64 vcc, exec, s[4:5]
	s_cbranch_vccnz .LBB0_473
	s_barrier
	s_branch .LBB0_473

.LBB0_818:
	v_lshrrev_b32_e32 v16, 1, v6
	v_and_b32_e32 v16, 24, v16
	s_sext_i32_i16 s58, s6
	s_add_u32 s6, s0, 0x1b400000
	v_and_b32_e32 v7, 15, v6
	v_lshlrev_b32_e32 v17, 1, v16
	v_lshlrev_b32_e32 v6, 2, v6
	s_addc_u32 s7, s1, 0
	v_lshl_or_b32 v140, s9, 6, v7
	v_lshl_or_b32 v7, v7, 6, v17
	s_lshl_b32 s0, s9, 13
	v_and_b32_e32 v6, 32, v6
	v_bitop3_b32 v141, v7, s0, v6 bitop3:0xde
	s_lshl_b32 s0, s10, 5
	s_and_b32 s10, s0, 0x60
	v_lshl_add_u64 v[8:9], s[20:21], 0, v[160:161]
	v_mov_b32_e32 v133, v161
	s_lshl_b32 s0, s10, 7
	s_add_i32 s45, s35, 0x18000
	v_lshl_add_u64 v[10:11], s[20:21], 0, v[132:133]
	v_mov_b32_e32 v129, v161
	v_bitop3_b32 v142, v7, s0, v6 bitop3:0xde
	v_lshl_add_u64 v[6:7], v[8:9], 0, s[40:41]
	s_mov_b32 m0, s45
	s_add_i32 s46, s35, 0x1a000
	v_lshl_add_u64 v[12:13], s[22:23], 0, v[128:129]
	v_mov_b32_e32 v131, v161
	s_waitcnt vmcnt(2)
	s_barrier
	global_load_lds_dwordx4 v[6:7], off
	v_lshl_add_u64 v[6:7], v[10:11], 0, s[40:41]
	s_mov_b32 m0, s46
	s_add_i32 s47, s35, 0x8000
	s_add_i32 s54, s35, 0xa000
	v_lshl_add_u64 v[14:15], s[22:23], 0, v[130:131]
	global_load_lds_dwordx4 v[6:7], off
	v_lshl_add_u64 v[6:7], v[12:13], 0, s[40:41]
	s_mov_b32 m0, s47
	s_add_u32 s0, s20, 0x80080
	global_load_lds_dwordx4 v[6:7], off
	v_lshl_add_u64 v[6:7], v[14:15], 0, s[40:41]
	s_mov_b32 m0, s54
	s_addc_u32 s1, s21, 0
	s_add_i32 s55, s35, 0x1c000
	global_load_lds_dwordx4 v[6:7], off
	v_lshl_add_u64 v[6:7], s[0:1], 0, v[160:161]
	s_mov_b32 m0, s55
	s_add_i32 s56, s35, 0x1e000
	global_load_lds_dwordx4 v[6:7], off
	v_lshl_add_u64 v[6:7], s[0:1], 0, v[132:133]
	s_mov_b32 m0, s56
	s_cmpk_lt_u32 s8, 0x100
	global_load_lds_dwordx4 v[6:7], off
	v_lshlrev_b32_e32 v6, 15, v3
	v_and_b32_e32 v6, 0xffff0000, v6
	v_lshl_add_u32 v4, v4, 12, v6
	v_and_b32_e32 v3, 1, v3
	v_lshl_or_b32 v3, v3, 6, v4
	v_lshl_add_u32 v134, v5, 1, v3
	v_lshlrev_b32_e32 v3, 15, v0
	v_and_b32_e32 v3, 0xffff0000, v3
	s_waitcnt vmcnt(6)
	v_lshl_add_u32 v1, v1, 12, v3
	v_and_b32_e32 v0, 1, v0
	v_lshl_or_b32 v0, v0, 6, v1
	s_cselect_b64 s[8:9], -1, 0
	v_or_b32_e32 v143, s10, v16
	v_mov_b32_e32 v135, v161
	v_lshl_add_u32 v136, v2, 1, v0
	v_mov_b32_e32 v137, v161
	s_mov_b32 s57, 0
	s_barrier
	s_mov_b32 s32, 0
	s_branch .LBB0_821

.LBB0_820:
	s_andn2_b64 vcc, exec, s[0:1]
	s_mov_b32 s58, s10
	s_mov_b32 s18, s12
	s_mov_b64 s[20:21], s[16:17]
	s_mov_b64 s[22:23], s[14:15]
	s_cbranch_vccz .LBB0_834
	s_mov_b32 s32, 1

.LBB0_828:
	v_or_b32_e32 v138, 0x10000, v142
	v_add_u32_e32 v139, 0x10400, v142
	ds_read_b128 v[144:147], v138
	ds_read_b128 v[148:151], v139
	v_add_u32_e32 v138, 0x10800, v142
	v_add_u32_e32 v139, 0x10c00, v142
	ds_read_b128 v[152:155], v138
	ds_read_b128 v[156:159], v139
	v_or_b32_e32 v138, 0x14000, v142
	v_add_u32_e32 v139, 0x14400, v142
	ds_read_b128 v[170:173], v138
	ds_read_b128 v[174:177], v139
	v_add_u32_e32 v138, 0x14800, v142
	v_add_u32_e32 v139, 0x14c00, v142
	ds_read_b128 v[178:181], v138
	ds_read_b128 v[182:185], v139
	s_add_u32 s22, s20, 0xfff80080
	s_addc_u32 s23, s21, -1
	s_cmp_eq_u32 s63, 28
	s_cselect_b32 s25, s13, s23
	s_cselect_b32 s24, s59, s22
	s_cselect_b32 s23, s11, s62
	s_cselect_b32 s22, s60, s61
	v_lshl_add_u64 v[138:139], s[20:21], 0, v[136:137]
	s_add_i32 m0, s35, 0xc000
	ds_read_b128 v[186:189], v141
	ds_read_b128 v[198:201], v141 offset:1024
	ds_read_b128 v[202:205], v141 offset:2048
	ds_read_b128 v[210:213], v141 offset:3072
	ds_read_b128 v[214:217], v141 offset:4096
	ds_read_b128 v[218:221], v141 offset:5120
	ds_read_b128 v[222:225], v141 offset:6144
	ds_read_b128 v[226:229], v141 offset:7168
	global_load_lds_dwordx4 v[138:139], off
	v_lshl_add_u64 v[138:139], s[20:21], 0, v[134:135]
	s_add_i32 m0, s35, 0xe000
	s_nop 0
	global_load_lds_dwordx4 v[138:139], off
	s_cmp_eq_u32 s32, 0
	s_cbranch_scc0 .Lmy_g5_alt0
	s_waitcnt vmcnt(8)
.Lmy_g5_bk0:
	s_waitcnt lgkmcnt(0)
	s_barrier
	s_setprio 1
	s_waitcnt lgkmcnt(0)
	v_mfma_f32_16x16x32_bf16 v[124:127], v[144:147], v[186:189], v[124:127]
	v_mfma_f32_16x16x32_bf16 v[120:123], v[152:155], v[186:189], v[120:123]
	v_mfma_f32_16x16x32_bf16 v[108:111], v[144:147], v[202:205], v[108:111]
	v_mfma_f32_16x16x32_bf16 v[104:107], v[152:155], v[202:205], v[104:107]
	v_mfma_f32_16x16x32_bf16 v[92:95], v[144:147], v[214:217], v[92:95]
	v_mfma_f32_16x16x32_bf16 v[88:91], v[152:155], v[214:217], v[88:91]
	v_mfma_f32_16x16x32_bf16 v[76:79], v[144:147], v[222:225], v[76:79]
	v_mfma_f32_16x16x32_bf16 v[72:75], v[152:155], v[222:225], v[72:75]
	v_mfma_f32_16x16x32_bf16 v[124:127], v[148:151], v[198:201], v[124:127]
	v_mfma_f32_16x16x32_bf16 v[120:123], v[156:159], v[198:201], v[120:123]
	v_mfma_f32_16x16x32_bf16 v[108:111], v[148:151], v[210:213], v[108:111]
	v_mfma_f32_16x16x32_bf16 v[104:107], v[156:159], v[210:213], v[104:107]
	v_mfma_f32_16x16x32_bf16 v[92:95], v[148:151], v[218:221], v[92:95]
	v_mfma_f32_16x16x32_bf16 v[88:91], v[156:159], v[218:221], v[88:91]
	v_mfma_f32_16x16x32_bf16 v[76:79], v[148:151], v[226:229], v[76:79]
	v_mfma_f32_16x16x32_bf16 v[72:75], v[156:159], v[226:229], v[72:75]
	s_setprio 0
	s_setprio 1
	v_mfma_f32_16x16x32_bf16 v[116:119], v[170:173], v[186:189], v[116:119]
	v_mfma_f32_16x16x32_bf16 v[112:115], v[178:181], v[186:189], v[112:115]
	v_mfma_f32_16x16x32_bf16 v[100:103], v[170:173], v[202:205], v[100:103]
	v_mfma_f32_16x16x32_bf16 v[96:99], v[178:181], v[202:205], v[96:99]
	v_mfma_f32_16x16x32_bf16 v[84:87], v[170:173], v[214:217], v[84:87]
	v_mfma_f32_16x16x32_bf16 v[80:83], v[178:181], v[214:217], v[80:83]
	v_mfma_f32_16x16x32_bf16 v[68:71], v[170:173], v[222:225], v[68:71]
	v_mfma_f32_16x16x32_bf16 v[64:67], v[178:181], v[222:225], v[64:67]
	v_mfma_f32_16x16x32_bf16 v[116:119], v[174:177], v[198:201], v[116:119]
	v_mfma_f32_16x16x32_bf16 v[112:115], v[182:185], v[198:201], v[112:115]
	v_mfma_f32_16x16x32_bf16 v[100:103], v[174:177], v[210:213], v[100:103]
	v_mfma_f32_16x16x32_bf16 v[96:99], v[182:185], v[210:213], v[96:99]
	v_mfma_f32_16x16x32_bf16 v[84:87], v[174:177], v[218:221], v[84:87]
	v_mfma_f32_16x16x32_bf16 v[80:83], v[182:185], v[218:221], v[80:83]
	v_mfma_f32_16x16x32_bf16 v[68:71], v[174:177], v[226:229], v[68:71]
	v_mfma_f32_16x16x32_bf16 v[64:67], v[182:185], v[226:229], v[64:67]
	s_setprio 0
	s_barrier
	s_mov_b32 m0, s19
	v_lshl_add_u64 v[138:139], s[22:23], 0, v[160:161]
	s_add_u32 s64, s22, 0x80000
	ds_read_b128 v[186:189], v141 offset:16384
	ds_read_b128 v[198:201], v141 offset:17408
	ds_read_b128 v[202:205], v141 offset:18432
	ds_read_b128 v[210:213], v141 offset:19456
	ds_read_b128 v[214:217], v141 offset:20480
	ds_read_b128 v[218:221], v141 offset:21504
	ds_read_b128 v[222:225], v141 offset:22528
	ds_read_b128 v[226:229], v141 offset:23552
	global_load_lds_dwordx4 v[138:139], off
	v_lshl_add_u64 v[190:191], s[22:23], 0, v[132:133]
	s_mov_b32 m0, s36
	s_addc_u32 s65, s23, 0
	global_load_lds_dwordx4 v[190:191], off
	v_lshl_add_u64 v[206:207], s[64:65], 0, v[160:161]
	s_mov_b32 m0, s37
	v_lshl_add_u64 v[208:209], s[24:25], 0, v[130:131]
	global_load_lds_dwordx4 v[206:207], off
	v_lshl_add_u64 v[206:207], s[64:65], 0, v[132:133]
	s_mov_b32 m0, s38
	s_nop 0
	global_load_lds_dwordx4 v[206:207], off
	v_lshl_add_u64 v[206:207], s[24:25], 0, v[128:129]
	s_mov_b32 m0, s35
	s_nop 0
	global_load_lds_dwordx4 v[206:207], off
	s_mov_b32 m0, s42
	s_nop 0
	global_load_lds_dwordx4 v[208:209], off
	s_cmp_eq_u32 s32, 0
	s_cbranch_scc0 .Lmy_g5_alt1
	s_waitcnt vmcnt(8)
.Lmy_g5_bk1:
	s_waitcnt lgkmcnt(0)
	s_barrier
	s_setprio 1
	s_waitcnt lgkmcnt(0)
	v_mfma_f32_16x16x32_bf16 v[60:63], v[144:147], v[186:189], v[60:63]
	v_mfma_f32_16x16x32_bf16 v[56:59], v[152:155], v[186:189], v[56:59]
	v_mfma_f32_16x16x32_bf16 v[44:47], v[144:147], v[202:205], v[44:47]
	v_mfma_f32_16x16x32_bf16 v[40:43], v[152:155], v[202:205], v[40:43]
	v_mfma_f32_16x16x32_bf16 v[28:31], v[144:147], v[214:217], v[28:31]
	v_mfma_f32_16x16x32_bf16 v[24:27], v[152:155], v[214:217], v[24:27]
	v_mfma_f32_16x16x32_bf16 v[12:15], v[144:147], v[222:225], v[12:15]
	v_mfma_f32_16x16x32_bf16 v[8:11], v[152:155], v[222:225], v[8:11]
	v_mfma_f32_16x16x32_bf16 v[60:63], v[148:151], v[198:201], v[60:63]
	v_mfma_f32_16x16x32_bf16 v[56:59], v[156:159], v[198:201], v[56:59]
	v_mfma_f32_16x16x32_bf16 v[44:47], v[148:151], v[210:213], v[44:47]
	v_mfma_f32_16x16x32_bf16 v[40:43], v[156:159], v[210:213], v[40:43]
	v_mfma_f32_16x16x32_bf16 v[28:31], v[148:151], v[218:221], v[28:31]
	v_mfma_f32_16x16x32_bf16 v[24:27], v[156:159], v[218:221], v[24:27]
	v_mfma_f32_16x16x32_bf16 v[12:15], v[148:151], v[226:229], v[12:15]
	v_mfma_f32_16x16x32_bf16 v[8:11], v[156:159], v[226:229], v[8:11]
	s_setprio 0
	s_setprio 1
	v_mfma_f32_16x16x32_bf16 v[52:55], v[170:173], v[186:189], v[52:55]
	v_mfma_f32_16x16x32_bf16 v[48:51], v[178:181], v[186:189], v[48:51]
	v_mfma_f32_16x16x32_bf16 v[36:39], v[170:173], v[202:205], v[36:39]
	v_mfma_f32_16x16x32_bf16 v[32:35], v[178:181], v[202:205], v[32:35]
	v_mfma_f32_16x16x32_bf16 v[20:23], v[170:173], v[214:217], v[20:23]
	v_mfma_f32_16x16x32_bf16 v[16:19], v[178:181], v[214:217], v[16:19]
	v_mfma_f32_16x16x32_bf16 v[4:7], v[170:173], v[222:225], v[4:7]
	v_mfma_f32_16x16x32_bf16 v[0:3], v[178:181], v[222:225], v[0:3]
	v_mfma_f32_16x16x32_bf16 v[52:55], v[174:177], v[198:201], v[52:55]
	v_mfma_f32_16x16x32_bf16 v[48:51], v[182:185], v[198:201], v[48:51]
	v_mfma_f32_16x16x32_bf16 v[36:39], v[174:177], v[210:213], v[36:39]
	v_mfma_f32_16x16x32_bf16 v[32:35], v[182:185], v[210:213], v[32:35]
	v_mfma_f32_16x16x32_bf16 v[20:23], v[174:177], v[218:221], v[20:23]
	v_mfma_f32_16x16x32_bf16 v[16:19], v[182:185], v[218:221], v[16:19]
	v_mfma_f32_16x16x32_bf16 v[4:7], v[174:177], v[226:229], v[4:7]
	v_mfma_f32_16x16x32_bf16 v[0:3], v[182:185], v[226:229], v[0:3]
	s_setprio 0
	s_barrier
	v_or_b32_e32 v144, 0x18000, v142
	v_add_u32_e32 v148, 0x18400, v142
	v_add_u32_e32 v152, 0x18800, v142
	v_add_u32_e32 v156, 0x18c00, v142
	v_or_b32_e32 v170, 0x1c000, v142
	v_add_u32_e32 v174, 0x1c400, v142
	v_add_u32_e32 v178, 0x1c800, v142
	v_add_u32_e32 v182, 0x1cc00, v142
	ds_read_b128 v[144:147], v144
	ds_read_b128 v[148:151], v148
	ds_read_b128 v[152:155], v152
	ds_read_b128 v[156:159], v156
	ds_read_b128 v[170:173], v170
	ds_read_b128 v[174:177], v174
	ds_read_b128 v[178:181], v178
	ds_read_b128 v[182:185], v182
	s_add_u32 s24, s24, 0x80000
	s_addc_u32 s25, s25, 0
	s_mov_b32 m0, s43
	v_lshl_add_u64 v[230:231], s[24:25], 0, v[128:129]
	ds_read_b128 v[186:189], v141 offset:32768
	ds_read_b128 v[198:201], v141 offset:33792
	ds_read_b128 v[202:205], v141 offset:34816
	ds_read_b128 v[210:213], v141 offset:35840
	ds_read_b128 v[214:217], v141 offset:36864
	ds_read_b128 v[218:221], v141 offset:37888
	ds_read_b128 v[222:225], v141 offset:38912
	ds_read_b128 v[226:229], v141 offset:39936
	global_load_lds_dwordx4 v[230:231], off
	v_lshl_add_u64 v[230:231], s[24:25], 0, v[130:131]
	s_mov_b32 m0, s44
	s_nop 0
	global_load_lds_dwordx4 v[230:231], off
	s_cmp_eq_u32 s32, 0
	s_cbranch_scc0 .Lmy_g5_alt2
	s_waitcnt vmcnt(8)
.Lmy_g5_bk2:
	s_waitcnt lgkmcnt(0)
	s_barrier
	s_setprio 1
	s_waitcnt lgkmcnt(0)
	v_mfma_f32_16x16x32_bf16 v[124:127], v[144:147], v[186:189], v[124:127]
	v_mfma_f32_16x16x32_bf16 v[120:123], v[152:155], v[186:189], v[120:123]
	v_mfma_f32_16x16x32_bf16 v[108:111], v[144:147], v[202:205], v[108:111]
	v_mfma_f32_16x16x32_bf16 v[104:107], v[152:155], v[202:205], v[104:107]
	v_mfma_f32_16x16x32_bf16 v[92:95], v[144:147], v[214:217], v[92:95]
	v_mfma_f32_16x16x32_bf16 v[88:91], v[152:155], v[214:217], v[88:91]
	v_mfma_f32_16x16x32_bf16 v[76:79], v[144:147], v[222:225], v[76:79]
	v_mfma_f32_16x16x32_bf16 v[72:75], v[152:155], v[222:225], v[72:75]
	v_mfma_f32_16x16x32_bf16 v[124:127], v[148:151], v[198:201], v[124:127]
	v_mfma_f32_16x16x32_bf16 v[120:123], v[156:159], v[198:201], v[120:123]
	v_mfma_f32_16x16x32_bf16 v[108:111], v[148:151], v[210:213], v[108:111]
	v_mfma_f32_16x16x32_bf16 v[104:107], v[156:159], v[210:213], v[104:107]
	v_mfma_f32_16x16x32_bf16 v[92:95], v[148:151], v[218:221], v[92:95]
	v_mfma_f32_16x16x32_bf16 v[88:91], v[156:159], v[218:221], v[88:91]
	v_mfma_f32_16x16x32_bf16 v[76:79], v[148:151], v[226:229], v[76:79]
	v_mfma_f32_16x16x32_bf16 v[72:75], v[156:159], v[226:229], v[72:75]
	s_setprio 0
	s_setprio 1
	v_mfma_f32_16x16x32_bf16 v[116:119], v[170:173], v[186:189], v[116:119]
	v_mfma_f32_16x16x32_bf16 v[112:115], v[178:181], v[186:189], v[112:115]
	v_mfma_f32_16x16x32_bf16 v[100:103], v[170:173], v[202:205], v[100:103]
	v_mfma_f32_16x16x32_bf16 v[96:99], v[178:181], v[202:205], v[96:99]
	v_mfma_f32_16x16x32_bf16 v[84:87], v[170:173], v[214:217], v[84:87]
	v_mfma_f32_16x16x32_bf16 v[80:83], v[178:181], v[214:217], v[80:83]
	v_mfma_f32_16x16x32_bf16 v[68:71], v[170:173], v[222:225], v[68:71]
	v_mfma_f32_16x16x32_bf16 v[64:67], v[178:181], v[222:225], v[64:67]
	v_mfma_f32_16x16x32_bf16 v[116:119], v[174:177], v[198:201], v[116:119]
	v_mfma_f32_16x16x32_bf16 v[112:115], v[182:185], v[198:201], v[112:115]
	v_mfma_f32_16x16x32_bf16 v[100:103], v[174:177], v[210:213], v[100:103]
	v_mfma_f32_16x16x32_bf16 v[96:99], v[182:185], v[210:213], v[96:99]
	v_mfma_f32_16x16x32_bf16 v[84:87], v[174:177], v[218:221], v[84:87]
	v_mfma_f32_16x16x32_bf16 v[80:83], v[182:185], v[218:221], v[80:83]
	v_mfma_f32_16x16x32_bf16 v[68:71], v[174:177], v[226:229], v[68:71]
	v_mfma_f32_16x16x32_bf16 v[64:67], v[182:185], v[226:229], v[64:67]
	s_setprio 0
	s_barrier
	s_mov_b32 m0, s45
	v_lshl_add_u64 v[138:139], v[138:139], 0, s[40:41]
	s_add_u32 s22, s22, 0x80080
	ds_read_b128 v[186:189], v141 offset:49152
	ds_read_b128 v[198:201], v141 offset:50176
	ds_read_b128 v[202:205], v141 offset:51200
	ds_read_b128 v[210:213], v141 offset:52224
	ds_read_b128 v[214:217], v141 offset:53248
	ds_read_b128 v[218:221], v141 offset:54272
	ds_read_b128 v[222:225], v141 offset:55296
	ds_read_b128 v[226:229], v141 offset:56320
	global_load_lds_dwordx4 v[138:139], off
	v_lshl_add_u64 v[138:139], v[190:191], 0, s[40:41]
	s_mov_b32 m0, s46
	s_addc_u32 s23, s23, 0
	global_load_lds_dwordx4 v[138:139], off
	v_lshl_add_u64 v[138:139], s[22:23], 0, v[160:161]
	s_mov_b32 m0, s55
	s_nop 0
	global_load_lds_dwordx4 v[138:139], off
	v_lshl_add_u64 v[138:139], s[22:23], 0, v[132:133]
	s_mov_b32 m0, s56
	s_nop 0
	global_load_lds_dwordx4 v[138:139], off
	v_lshl_add_u64 v[138:139], v[206:207], 0, s[40:41]
	s_mov_b32 m0, s47
	s_nop 0
	global_load_lds_dwordx4 v[138:139], off
	v_lshl_add_u64 v[138:139], v[208:209], 0, s[40:41]
	s_mov_b32 m0, s54
	s_nop 0
	global_load_lds_dwordx4 v[138:139], off
	s_waitcnt vmcnt(8)
	s_waitcnt lgkmcnt(0)
	s_barrier
	s_setprio 1
	s_waitcnt lgkmcnt(0)
	v_mfma_f32_16x16x32_bf16 v[60:63], v[144:147], v[186:189], v[60:63]
	v_mfma_f32_16x16x32_bf16 v[56:59], v[152:155], v[186:189], v[56:59]
	v_mfma_f32_16x16x32_bf16 v[44:47], v[144:147], v[202:205], v[44:47]
	v_mfma_f32_16x16x32_bf16 v[40:43], v[152:155], v[202:205], v[40:43]
	v_mfma_f32_16x16x32_bf16 v[28:31], v[144:147], v[214:217], v[28:31]
	v_mfma_f32_16x16x32_bf16 v[24:27], v[152:155], v[214:217], v[24:27]
	v_mfma_f32_16x16x32_bf16 v[12:15], v[144:147], v[222:225], v[12:15]
	v_mfma_f32_16x16x32_bf16 v[8:11], v[152:155], v[222:225], v[8:11]
	v_mfma_f32_16x16x32_bf16 v[60:63], v[148:151], v[198:201], v[60:63]
	v_mfma_f32_16x16x32_bf16 v[56:59], v[156:159], v[198:201], v[56:59]
	v_mfma_f32_16x16x32_bf16 v[44:47], v[148:151], v[210:213], v[44:47]
	v_mfma_f32_16x16x32_bf16 v[40:43], v[156:159], v[210:213], v[40:43]
	v_mfma_f32_16x16x32_bf16 v[28:31], v[148:151], v[218:221], v[28:31]
	v_mfma_f32_16x16x32_bf16 v[24:27], v[156:159], v[218:221], v[24:27]
	v_mfma_f32_16x16x32_bf16 v[12:15], v[148:151], v[226:229], v[12:15]
	v_mfma_f32_16x16x32_bf16 v[8:11], v[156:159], v[226:229], v[8:11]
	s_setprio 0
	s_setprio 1
	v_mfma_f32_16x16x32_bf16 v[52:55], v[170:173], v[186:189], v[52:55]
	v_mfma_f32_16x16x32_bf16 v[48:51], v[178:181], v[186:189], v[48:51]
	v_mfma_f32_16x16x32_bf16 v[36:39], v[170:173], v[202:205], v[36:39]
	v_mfma_f32_16x16x32_bf16 v[32:35], v[178:181], v[202:205], v[32:35]
	v_mfma_f32_16x16x32_bf16 v[20:23], v[170:173], v[214:217], v[20:23]
	v_mfma_f32_16x16x32_bf16 v[16:19], v[178:181], v[214:217], v[16:19]
	v_mfma_f32_16x16x32_bf16 v[4:7], v[170:173], v[222:225], v[4:7]
	v_mfma_f32_16x16x32_bf16 v[0:3], v[178:181], v[222:225], v[0:3]
	v_mfma_f32_16x16x32_bf16 v[52:55], v[174:177], v[198:201], v[52:55]
	v_mfma_f32_16x16x32_bf16 v[48:51], v[182:185], v[198:201], v[48:51]
	v_mfma_f32_16x16x32_bf16 v[36:39], v[174:177], v[210:213], v[36:39]
	v_mfma_f32_16x16x32_bf16 v[32:35], v[182:185], v[210:213], v[32:35]
	v_mfma_f32_16x16x32_bf16 v[20:23], v[174:177], v[218:221], v[20:23]
	v_mfma_f32_16x16x32_bf16 v[16:19], v[182:185], v[218:221], v[16:19]
	v_mfma_f32_16x16x32_bf16 v[4:7], v[174:177], v[226:229], v[4:7]
	v_mfma_f32_16x16x32_bf16 v[0:3], v[182:185], v[226:229], v[0:3]
	s_setprio 0
	s_barrier
	s_add_i32 s63, s63, 2
	s_add_u32 s61, s61, 0x100
	s_addc_u32 s62, s62, 0
	s_add_u32 s20, s20, 0x100
	s_addc_u32 s21, s21, 0
	s_mov_b32 s32, 0
	s_cmp_gt_u32 s63, 29
	s_cbranch_scc0 .LBB0_828
	s_branch .Lmy_g5_cont

.Lmy_g5_cont:
	v_readlane_b32 s62, v253, 42
	s_and_b64 vcc, exec, s[8:9]
	s_movk_i32 s60, 0x2000
	v_readlane_b32 s63, v253, 43
	s_cbranch_vccz .LBB0_831
	s_barrier
.LBB0_831:
	v_lshl_add_u32 v144, s18, 8, v140
	v_max_f32_e32 v120, v120, v120
	v_ashrrev_i32_e32 v145, 31, v144
	v_max_f32_e32 v120, 0, v120
	v_max_f32_e32 v121, v121, v121
	v_max_f32_e32 v122, v122, v122
	v_lshl_or_b32 v138, s58, 8, v143
	v_lshlrev_b64 v[146:147], 14, v[144:145]
	v_mul_f32_e32 v145, v120, v120
	v_max_f32_e32 v120, v125, v125
	v_max_f32_e32 v121, 0, v121
	v_max_f32_e32 v122, 0, v122
	v_ashrrev_i32_e32 v139, 31, v138
	v_max_f32_e32 v124, v124, v124
	v_max_f32_e32 v120, 0, v120
	v_mul_f32_e32 v125, v121, v121
	v_max_f32_e32 v121, v126, v126
	v_mul_f32_e32 v126, v122, v122
	v_max_f32_e32 v122, v127, v127
	v_max_f32_e32 v123, v123, v123
	v_lshl_add_u64 v[146:147], s[6:7], 0, v[146:147]
	v_lshlrev_b64 v[148:149], 1, v[138:139]
	v_max_f32_e32 v124, 0, v124
	v_mul_f32_e32 v120, v120, v120
	v_max_f32_e32 v121, 0, v121
	v_max_f32_e32 v122, 0, v122
	v_max_f32_e32 v123, 0, v123
	v_max_f32_e32 v112, v112, v112
	v_lshl_add_u64 v[138:139], v[146:147], 0, v[148:149]
	v_mul_f32_e32 v124, v124, v124
	v_mul_f32_e32 v121, v121, v121
	v_mul_f32_e32 v122, v122, v122
	v_mul_f32_e32 v123, v123, v123
	v_cvt_pk_bf16_f32 v120, v124, v120
	v_max_f32_e32 v112, 0, v112
	v_max_f32_e32 v113, v113, v113
	v_max_f32_e32 v114, v114, v114
	v_cvt_pk_bf16_f32 v121, v121, v122
	v_cvt_pk_bf16_f32 v122, v145, v125
	v_cvt_pk_bf16_f32 v123, v126, v123
	global_store_dwordx4 v[138:139], v[120:123], off
	v_max_f32_e32 v113, 0, v113
	v_max_f32_e32 v114, 0, v114
	v_mul_f32_e32 v120, v112, v112
	v_max_f32_e32 v112, v117, v117
	v_max_f32_e32 v116, v116, v116
	v_max_f32_e32 v112, 0, v112
	v_mul_f32_e32 v117, v113, v113
	v_max_f32_e32 v113, v118, v118
	v_mul_f32_e32 v118, v114, v114
	v_max_f32_e32 v114, v119, v119
	v_max_f32_e32 v115, v115, v115
	v_max_f32_e32 v116, 0, v116
	v_mul_f32_e32 v112, v112, v112
	v_max_f32_e32 v113, 0, v113
	v_max_f32_e32 v114, 0, v114
	v_max_f32_e32 v115, 0, v115
	v_mul_f32_e32 v116, v116, v116
	v_mul_f32_e32 v113, v113, v113
	v_mul_f32_e32 v114, v114, v114
	v_mul_f32_e32 v115, v115, v115
	v_cvt_pk_bf16_f32 v112, v116, v112
	v_max_f32_e32 v104, v104, v104
	v_cvt_pk_bf16_f32 v113, v113, v114
	v_cvt_pk_bf16_f32 v114, v120, v117
	v_cvt_pk_bf16_f32 v115, v118, v115
	global_store_dwordx4 v[138:139], v[112:115], off offset:256
	v_max_f32_e32 v104, 0, v104
	v_max_f32_e32 v105, v105, v105
	v_or_b32_e32 v112, 16, v144
	v_max_f32_e32 v106, v106, v106
	v_ashrrev_i32_e32 v113, 31, v112
	v_mul_f32_e32 v114, v104, v104
	v_max_f32_e32 v104, v109, v109
	v_max_f32_e32 v105, 0, v105
	v_max_f32_e32 v106, 0, v106
	v_lshlrev_b64 v[112:113], 14, v[112:113]
	v_max_f32_e32 v108, v108, v108
	v_max_f32_e32 v104, 0, v104
	v_mul_f32_e32 v109, v105, v105
	v_max_f32_e32 v105, v110, v110
	v_mul_f32_e32 v110, v106, v106
	v_max_f32_e32 v106, v111, v111
	v_max_f32_e32 v107, v107, v107
	v_lshl_add_u64 v[112:113], s[6:7], 0, v[112:113]
	v_max_f32_e32 v108, 0, v108
	v_mul_f32_e32 v104, v104, v104
	v_max_f32_e32 v105, 0, v105
	v_max_f32_e32 v106, 0, v106
	v_max_f32_e32 v107, 0, v107
	v_max_f32_e32 v96, v96, v96
	v_lshl_add_u64 v[112:113], v[112:113], 0, v[148:149]
	v_mul_f32_e32 v108, v108, v108
	v_mul_f32_e32 v105, v105, v105
	v_mul_f32_e32 v106, v106, v106
	v_mul_f32_e32 v107, v107, v107
	v_cvt_pk_bf16_f32 v104, v108, v104
	v_max_f32_e32 v96, 0, v96
	v_max_f32_e32 v97, v97, v97
	v_max_f32_e32 v98, v98, v98
	v_cvt_pk_bf16_f32 v105, v105, v106
	v_cvt_pk_bf16_f32 v106, v114, v109
	v_cvt_pk_bf16_f32 v107, v110, v107
	global_store_dwordx4 v[112:113], v[104:107], off
	v_max_f32_e32 v97, 0, v97
	v_max_f32_e32 v98, 0, v98
	v_mul_f32_e32 v104, v96, v96
	v_max_f32_e32 v96, v101, v101
	v_max_f32_e32 v100, v100, v100
	v_max_f32_e32 v96, 0, v96
	v_mul_f32_e32 v101, v97, v97
	v_max_f32_e32 v97, v102, v102
	v_mul_f32_e32 v102, v98, v98
	v_max_f32_e32 v98, v103, v103
	v_max_f32_e32 v99, v99, v99
	v_max_f32_e32 v100, 0, v100
	v_mul_f32_e32 v96, v96, v96
	v_max_f32_e32 v97, 0, v97
	v_max_f32_e32 v98, 0, v98
	v_max_f32_e32 v99, 0, v99
	v_mul_f32_e32 v100, v100, v100
	v_mul_f32_e32 v97, v97, v97
	v_mul_f32_e32 v98, v98, v98
	v_mul_f32_e32 v99, v99, v99
	v_cvt_pk_bf16_f32 v96, v100, v96
	v_max_f32_e32 v88, v88, v88
	v_cvt_pk_bf16_f32 v97, v97, v98
	v_cvt_pk_bf16_f32 v98, v104, v101
	v_cvt_pk_bf16_f32 v99, v102, v99
	global_store_dwordx4 v[112:113], v[96:99], off offset:256
	v_max_f32_e32 v88, 0, v88
	v_max_f32_e32 v89, v89, v89
	v_or_b32_e32 v96, 32, v144
	v_max_f32_e32 v90, v90, v90
	v_ashrrev_i32_e32 v97, 31, v96
	v_mul_f32_e32 v98, v88, v88
	v_max_f32_e32 v88, v93, v93
	v_max_f32_e32 v89, 0, v89
	v_max_f32_e32 v90, 0, v90
	v_lshlrev_b64 v[96:97], 14, v[96:97]
	v_max_f32_e32 v92, v92, v92
	v_max_f32_e32 v88, 0, v88
	v_mul_f32_e32 v93, v89, v89
	v_max_f32_e32 v89, v94, v94
	v_mul_f32_e32 v94, v90, v90
	v_max_f32_e32 v90, v95, v95
	v_max_f32_e32 v91, v91, v91
	v_lshl_add_u64 v[96:97], s[6:7], 0, v[96:97]
	v_max_f32_e32 v92, 0, v92
	v_mul_f32_e32 v88, v88, v88
	v_max_f32_e32 v89, 0, v89
	v_max_f32_e32 v90, 0, v90
	v_max_f32_e32 v91, 0, v91
	v_max_f32_e32 v80, v80, v80
	v_lshl_add_u64 v[96:97], v[96:97], 0, v[148:149]
	v_mul_f32_e32 v92, v92, v92
	v_mul_f32_e32 v89, v89, v89
	v_mul_f32_e32 v90, v90, v90
	v_mul_f32_e32 v91, v91, v91
	v_cvt_pk_bf16_f32 v88, v92, v88
	v_max_f32_e32 v80, 0, v80
	v_max_f32_e32 v81, v81, v81
	v_max_f32_e32 v82, v82, v82
	v_cvt_pk_bf16_f32 v89, v89, v90
	v_cvt_pk_bf16_f32 v90, v98, v93
	v_cvt_pk_bf16_f32 v91, v94, v91
	global_store_dwordx4 v[96:97], v[88:91], off
	v_max_f32_e32 v81, 0, v81
	v_max_f32_e32 v82, 0, v82
	v_mul_f32_e32 v88, v80, v80
	v_max_f32_e32 v80, v85, v85
	v_max_f32_e32 v84, v84, v84
	v_max_f32_e32 v80, 0, v80
	v_mul_f32_e32 v85, v81, v81
	v_max_f32_e32 v81, v86, v86
	v_mul_f32_e32 v86, v82, v82
	v_max_f32_e32 v82, v87, v87
	v_max_f32_e32 v83, v83, v83
	v_max_f32_e32 v84, 0, v84
	v_mul_f32_e32 v80, v80, v80
	v_max_f32_e32 v81, 0, v81
	v_max_f32_e32 v82, 0, v82
	v_max_f32_e32 v83, 0, v83
	v_mul_f32_e32 v84, v84, v84
	v_mul_f32_e32 v81, v81, v81
	v_mul_f32_e32 v82, v82, v82
	v_mul_f32_e32 v83, v83, v83
	v_cvt_pk_bf16_f32 v80, v84, v80
	v_max_f32_e32 v72, v72, v72
	v_cvt_pk_bf16_f32 v81, v81, v82
	v_cvt_pk_bf16_f32 v82, v88, v85
	v_cvt_pk_bf16_f32 v83, v86, v83
	global_store_dwordx4 v[96:97], v[80:83], off offset:256
	v_max_f32_e32 v72, 0, v72
	v_max_f32_e32 v73, v73, v73
	v_or_b32_e32 v80, 48, v144
	v_max_f32_e32 v74, v74, v74
	v_ashrrev_i32_e32 v81, 31, v80
	v_mul_f32_e32 v82, v72, v72
	v_max_f32_e32 v72, v77, v77
	v_max_f32_e32 v73, 0, v73
	v_max_f32_e32 v74, 0, v74
	v_lshlrev_b64 v[80:81], 14, v[80:81]
	v_max_f32_e32 v76, v76, v76
	v_max_f32_e32 v72, 0, v72
	v_mul_f32_e32 v77, v73, v73
	v_max_f32_e32 v73, v78, v78
	v_mul_f32_e32 v78, v74, v74
	v_max_f32_e32 v74, v79, v79
	v_max_f32_e32 v75, v75, v75
	v_lshl_add_u64 v[80:81], s[6:7], 0, v[80:81]
	v_max_f32_e32 v76, 0, v76
	v_mul_f32_e32 v72, v72, v72
	v_max_f32_e32 v73, 0, v73
	v_max_f32_e32 v74, 0, v74
	v_max_f32_e32 v75, 0, v75
	v_max_f32_e32 v64, v64, v64
	v_max_f32_e32 v65, v65, v65
	v_max_f32_e32 v66, v66, v66
	v_lshl_add_u64 v[80:81], v[80:81], 0, v[148:149]
	v_mul_f32_e32 v76, v76, v76
	v_mul_f32_e32 v73, v73, v73
	v_mul_f32_e32 v74, v74, v74
	v_mul_f32_e32 v75, v75, v75
	v_cvt_pk_bf16_f32 v72, v76, v72
	v_max_f32_e32 v64, 0, v64
	v_max_f32_e32 v65, 0, v65
	v_max_f32_e32 v66, 0, v66
	v_cvt_pk_bf16_f32 v73, v73, v74
	v_cvt_pk_bf16_f32 v74, v82, v77
	v_cvt_pk_bf16_f32 v75, v78, v75
	global_store_dwordx4 v[80:81], v[72:75], off
	v_max_f32_e32 v68, v68, v68
	v_max_f32_e32 v67, v67, v67
	v_mul_f32_e32 v72, v64, v64
	v_max_f32_e32 v64, v69, v69
	v_mul_f32_e32 v69, v65, v65
	v_max_f32_e32 v65, v70, v70
	v_mul_f32_e32 v70, v66, v66
	v_max_f32_e32 v66, v71, v71
	v_max_f32_e32 v64, 0, v64
	v_max_f32_e32 v65, 0, v65
	v_max_f32_e32 v66, 0, v66
	v_max_f32_e32 v68, 0, v68
	v_mul_f32_e32 v64, v64, v64
	v_mul_f32_e32 v65, v65, v65
	v_max_f32_e32 v67, 0, v67
	v_mul_f32_e32 v66, v66, v66
	v_max_f32_e32 v56, v56, v56
	v_mul_f32_e32 v68, v68, v68
	v_mul_f32_e32 v67, v67, v67
	v_cvt_pk_bf16_f32 v64, v68, v64
	v_cvt_pk_bf16_f32 v65, v65, v66
	v_cvt_pk_bf16_f32 v66, v72, v69
	v_max_f32_e32 v56, 0, v56
	v_max_f32_e32 v57, v57, v57
	v_max_f32_e32 v58, v58, v58
	v_cvt_pk_bf16_f32 v67, v70, v67
	global_store_dwordx4 v[80:81], v[64:67], off offset:256
	v_max_f32_e32 v60, v60, v60
	v_max_f32_e32 v57, 0, v57
	v_mul_f32_e32 v66, v56, v56
	v_max_f32_e32 v56, v61, v61
	v_max_f32_e32 v58, 0, v58
	v_max_f32_e32 v60, 0, v60
	v_max_f32_e32 v56, 0, v56
	v_mul_f32_e32 v61, v57, v57
	v_max_f32_e32 v57, v62, v62
	v_mul_f32_e32 v62, v58, v58
	v_max_f32_e32 v58, v63, v63
	v_mul_f32_e32 v60, v60, v60
	v_mul_f32_e32 v56, v56, v56
	v_max_f32_e32 v57, 0, v57
	v_max_f32_e32 v58, 0, v58
	v_max_f32_e32 v59, v59, v59
	s_mov_b32 s11, 0x200000
	v_mul_f32_e32 v57, v57, v57
	v_max_f32_e32 v59, 0, v59
	v_mul_f32_e32 v58, v58, v58
	v_cvt_pk_bf16_f32 v56, v60, v56
	v_add_co_u32_e32 v60, vcc, s11, v138
	v_max_f32_e32 v48, v48, v48
	v_max_f32_e32 v49, v49, v49
	v_max_f32_e32 v50, v50, v50
	v_mul_f32_e32 v59, v59, v59
	v_cvt_pk_bf16_f32 v57, v57, v58
	v_cvt_pk_bf16_f32 v58, v66, v61
	v_addc_co_u32_e32 v61, vcc, 0, v139, vcc
	v_max_f32_e32 v48, 0, v48
	v_max_f32_e32 v49, 0, v49
	v_max_f32_e32 v50, 0, v50
	v_cvt_pk_bf16_f32 v59, v62, v59
	global_store_dwordx4 v[60:61], v[56:59], off
	v_max_f32_e32 v52, v52, v52
	v_max_f32_e32 v51, v51, v51
	v_mul_f32_e32 v56, v48, v48
	v_max_f32_e32 v48, v53, v53
	v_mul_f32_e32 v53, v49, v49
	v_max_f32_e32 v49, v54, v54
	v_mul_f32_e32 v54, v50, v50
	v_max_f32_e32 v50, v55, v55
	v_max_f32_e32 v48, 0, v48
	v_max_f32_e32 v49, 0, v49
	v_max_f32_e32 v50, 0, v50
	s_mov_b64 s[20:21], 0x200000
	v_max_f32_e32 v52, 0, v52
	v_mul_f32_e32 v48, v48, v48
	v_mul_f32_e32 v49, v49, v49
	v_max_f32_e32 v51, 0, v51
	v_mul_f32_e32 v50, v50, v50
	v_max_f32_e32 v40, v40, v40
	v_lshl_add_u64 v[64:65], v[138:139], 0, s[20:21]
	v_mul_f32_e32 v52, v52, v52
	v_mul_f32_e32 v51, v51, v51
	v_cvt_pk_bf16_f32 v48, v52, v48
	v_cvt_pk_bf16_f32 v49, v49, v50
	v_cvt_pk_bf16_f32 v50, v56, v53
	v_max_f32_e32 v40, 0, v40
	v_max_f32_e32 v41, v41, v41
	v_max_f32_e32 v42, v42, v42
	v_cvt_pk_bf16_f32 v51, v54, v51
	global_store_dwordx4 v[64:65], v[48:51], off offset:256
	v_max_f32_e32 v44, v44, v44
	v_max_f32_e32 v41, 0, v41
	v_mul_f32_e32 v50, v40, v40
	v_max_f32_e32 v40, v45, v45
	v_max_f32_e32 v42, 0, v42
	v_max_f32_e32 v44, 0, v44
	v_max_f32_e32 v40, 0, v40
	v_mul_f32_e32 v45, v41, v41
	v_max_f32_e32 v41, v46, v46
	v_mul_f32_e32 v46, v42, v42
	v_max_f32_e32 v42, v47, v47
	v_mul_f32_e32 v44, v44, v44
	v_mul_f32_e32 v40, v40, v40
	v_max_f32_e32 v41, 0, v41
	v_max_f32_e32 v42, 0, v42
	v_max_f32_e32 v43, v43, v43
	s_mov_b32 s11, 0x240000
	v_mul_f32_e32 v41, v41, v41
	v_max_f32_e32 v43, 0, v43
	v_mul_f32_e32 v42, v42, v42
	v_cvt_pk_bf16_f32 v40, v44, v40
	v_add_co_u32_e32 v44, vcc, s11, v138
	v_max_f32_e32 v32, v32, v32
	v_max_f32_e32 v33, v33, v33
	v_max_f32_e32 v34, v34, v34
	v_mul_f32_e32 v43, v43, v43
	v_cvt_pk_bf16_f32 v41, v41, v42
	v_cvt_pk_bf16_f32 v42, v50, v45
	v_addc_co_u32_e32 v45, vcc, 0, v139, vcc
	v_max_f32_e32 v32, 0, v32
	v_max_f32_e32 v33, 0, v33
	v_max_f32_e32 v34, 0, v34
	v_cvt_pk_bf16_f32 v43, v46, v43
	global_store_dwordx4 v[44:45], v[40:43], off
	v_max_f32_e32 v36, v36, v36
	v_max_f32_e32 v35, v35, v35
	v_mul_f32_e32 v40, v32, v32
	v_max_f32_e32 v32, v37, v37
	v_mul_f32_e32 v37, v33, v33
	v_max_f32_e32 v33, v38, v38
	v_mul_f32_e32 v38, v34, v34
	v_max_f32_e32 v34, v39, v39
	v_max_f32_e32 v32, 0, v32
	v_max_f32_e32 v33, 0, v33
	v_max_f32_e32 v34, 0, v34
	s_mov_b64 s[20:21], 0x240000
	v_max_f32_e32 v36, 0, v36
	v_mul_f32_e32 v32, v32, v32
	v_mul_f32_e32 v33, v33, v33
	v_max_f32_e32 v35, 0, v35
	v_mul_f32_e32 v34, v34, v34
	v_max_f32_e32 v24, v24, v24
	v_lshl_add_u64 v[48:49], v[138:139], 0, s[20:21]
	v_mul_f32_e32 v36, v36, v36
	v_mul_f32_e32 v35, v35, v35
	v_cvt_pk_bf16_f32 v32, v36, v32
	v_cvt_pk_bf16_f32 v33, v33, v34
	v_cvt_pk_bf16_f32 v34, v40, v37
	v_max_f32_e32 v24, 0, v24
	v_max_f32_e32 v25, v25, v25
	v_max_f32_e32 v26, v26, v26
	v_cvt_pk_bf16_f32 v35, v38, v35
	global_store_dwordx4 v[48:49], v[32:35], off offset:256
	v_max_f32_e32 v28, v28, v28
	v_max_f32_e32 v25, 0, v25
	v_mul_f32_e32 v34, v24, v24
	v_max_f32_e32 v24, v29, v29
	v_max_f32_e32 v26, 0, v26
	v_max_f32_e32 v28, 0, v28
	v_max_f32_e32 v24, 0, v24
	v_mul_f32_e32 v29, v25, v25
	v_max_f32_e32 v25, v30, v30
	v_mul_f32_e32 v30, v26, v26
	v_max_f32_e32 v26, v31, v31
	v_mul_f32_e32 v28, v28, v28
	v_mul_f32_e32 v24, v24, v24
	v_max_f32_e32 v25, 0, v25
	v_max_f32_e32 v26, 0, v26
	v_max_f32_e32 v27, v27, v27
	s_mov_b32 s11, 0x280000
	v_mul_f32_e32 v25, v25, v25
	v_max_f32_e32 v27, 0, v27
	v_mul_f32_e32 v26, v26, v26
	v_cvt_pk_bf16_f32 v24, v28, v24
	v_add_co_u32_e32 v28, vcc, s11, v138
	v_max_f32_e32 v16, v16, v16
	v_max_f32_e32 v17, v17, v17
	v_max_f32_e32 v18, v18, v18
	v_mul_f32_e32 v27, v27, v27
	v_cvt_pk_bf16_f32 v25, v25, v26
	v_cvt_pk_bf16_f32 v26, v34, v29
	v_addc_co_u32_e32 v29, vcc, 0, v139, vcc
	v_max_f32_e32 v16, 0, v16
	v_max_f32_e32 v17, 0, v17
	v_max_f32_e32 v18, 0, v18
	v_cvt_pk_bf16_f32 v27, v30, v27
	global_store_dwordx4 v[28:29], v[24:27], off
	v_max_f32_e32 v20, v20, v20
	v_max_f32_e32 v19, v19, v19
	v_mul_f32_e32 v24, v16, v16
	v_max_f32_e32 v16, v21, v21
	v_mul_f32_e32 v21, v17, v17
	v_max_f32_e32 v17, v22, v22
	v_mul_f32_e32 v22, v18, v18
	v_max_f32_e32 v18, v23, v23
	v_max_f32_e32 v16, 0, v16
	v_max_f32_e32 v17, 0, v17
	v_max_f32_e32 v18, 0, v18
	s_mov_b64 s[20:21], 0x280000
	v_max_f32_e32 v20, 0, v20
	v_mul_f32_e32 v16, v16, v16
	v_mul_f32_e32 v17, v17, v17
	v_max_f32_e32 v19, 0, v19
	v_mul_f32_e32 v18, v18, v18
	v_max_f32_e32 v8, v8, v8
	v_lshl_add_u64 v[32:33], v[138:139], 0, s[20:21]
	v_mul_f32_e32 v20, v20, v20
	v_mul_f32_e32 v19, v19, v19
	v_cvt_pk_bf16_f32 v16, v20, v16
	v_cvt_pk_bf16_f32 v17, v17, v18
	v_cvt_pk_bf16_f32 v18, v24, v21
	v_max_f32_e32 v8, 0, v8
	v_max_f32_e32 v9, v9, v9
	v_max_f32_e32 v10, v10, v10
	v_cvt_pk_bf16_f32 v19, v22, v19
	global_store_dwordx4 v[32:33], v[16:19], off offset:256
	v_max_f32_e32 v12, v12, v12
	v_max_f32_e32 v9, 0, v9
	v_mul_f32_e32 v18, v8, v8
	v_max_f32_e32 v8, v13, v13
	v_max_f32_e32 v10, 0, v10
	v_max_f32_e32 v12, 0, v12
	v_max_f32_e32 v8, 0, v8
	v_mul_f32_e32 v13, v9, v9
	v_max_f32_e32 v9, v14, v14
	v_mul_f32_e32 v14, v10, v10
	v_max_f32_e32 v10, v15, v15
	v_mul_f32_e32 v12, v12, v12
	v_mul_f32_e32 v8, v8, v8
	v_max_f32_e32 v9, 0, v9
	v_max_f32_e32 v10, 0, v10
	v_max_f32_e32 v11, v11, v11
	s_mov_b32 s11, 0x2c0000
	v_mul_f32_e32 v9, v9, v9
	v_max_f32_e32 v11, 0, v11
	v_mul_f32_e32 v10, v10, v10
	v_cvt_pk_bf16_f32 v8, v12, v8
	v_add_co_u32_e32 v12, vcc, s11, v138
	v_max_f32_e32 v0, v0, v0
	v_max_f32_e32 v1, v1, v1
	v_max_f32_e32 v2, v2, v2
	v_mul_f32_e32 v11, v11, v11
	v_cvt_pk_bf16_f32 v9, v9, v10
	v_cvt_pk_bf16_f32 v10, v18, v13
	v_addc_co_u32_e32 v13, vcc, 0, v139, vcc
	v_max_f32_e32 v0, 0, v0
	v_max_f32_e32 v1, 0, v1
	v_max_f32_e32 v2, 0, v2
	v_cvt_pk_bf16_f32 v11, v14, v11
	global_store_dwordx4 v[12:13], v[8:11], off
	v_max_f32_e32 v3, v3, v3
	s_mov_b64 s[20:21], 0x2c0000
	v_mul_f32_e32 v8, v0, v0
	v_max_f32_e32 v0, v5, v5
	v_mul_f32_e32 v5, v1, v1
	v_max_f32_e32 v1, v6, v6
	v_mul_f32_e32 v6, v2, v2
	v_max_f32_e32 v2, v7, v7
	v_max_f32_e32 v4, v4, v4
	v_max_f32_e32 v0, 0, v0
	v_max_f32_e32 v1, 0, v1
	v_max_f32_e32 v2, 0, v2
	v_max_f32_e32 v3, 0, v3
	v_lshl_add_u64 v[16:17], v[138:139], 0, s[20:21]
	v_max_f32_e32 v4, 0, v4
	v_mul_f32_e32 v0, v0, v0
	v_mul_f32_e32 v1, v1, v1
	v_mul_f32_e32 v2, v2, v2
	v_mul_f32_e32 v3, v3, v3
	s_andn2_b64 vcc, exec, s[0:1]
	s_mov_b64 s[0:1], -1
	v_mul_f32_e32 v4, v4, v4
	v_cvt_pk_bf16_f32 v0, v4, v0
	v_cvt_pk_bf16_f32 v1, v1, v2
	v_cvt_pk_bf16_f32 v2, v8, v5
	v_cvt_pk_bf16_f32 v3, v6, v3
	global_store_dwordx4 v[16:17], v[0:3], off offset:256
	s_cbranch_vccnz .LBB0_820
	s_andn2_b64 vcc, exec, s[4:5]
	s_cbranch_vccnz .LBB0_819
	s_barrier
	s_branch .LBB0_819
